# G1 item body: counted waits for the prefetched k/vT loads no longer wait for the b-table / decay store acknowledgements (per-wave store flag selects the count)
# baseline (speedup 1.0000x reference)
; __device__ __forceinline__ unsigned cvt_pk_bf16(float lo, float hi) { unsigned r; asm volatile("v_cvt_pk_bf16_f32 %0, %1, %2" : "=v"(r) : "v"(lo), "v"(hi)); return r; }
; __device__ __forceinline__ float bf1(bf16_t b) { return __uint_as_float(((unsigned)b) << 16); }
; __device__ __forceinline__ Item decode_item(int it) { Item I; if (it < 1024) { const int b = it >> 8; I.h = (it >> 6) & 3; I.row0 = b * SEQ + (it & 63) * 64; I.L = 64; } else { const int j = it - 1024; I.h = j & 3; I.row0 = MP_ROWS + (j >> 2) * 16; I.L = 16; } I.j = it; return I; }
; __device__ __forceinline__ void compute_b(const Params& P, const Item& I, unsigned char* lds) {
;     ...
;     for (int q = 0; q < 3; ++q) if (q < tq) off += qt[q * 128 + dk];
; #pragma unroll
;     for (int i = 0; i < 16; ++i) bsh[(tq * 16 + i) * 128 + dk] = bl[i] + off;
;     __syncthreads();
; }
; __device__ __forceinline__ void gla_g1(const Params& P, unsigned char* lds) {
;     const int tid = threadIdx.x, wid = tid >> 6, lane = tid & 63, fr = lane & 15, fq = lane >> 4;
;     const bf16_t* kg = (const bf16_t*)(P.ws + O_K); const bf16_t* vT = (const bf16_t*)(P.ws + O_VT);
;     bf16_t* KVT = (bf16_t*)(P.ws + O_KVT); float* dec = (float*)(P.ws + O_DEC);
;     const float* bsh = (const float*)(lds + L_BSH); bf16_t* kT = (bf16_t*)(lds + L_KT);
;     for (int it = blockIdx.x; it < NITEM; it += gridDim.x) {
;         const Item I = decode_item(it);
;         compute_b(P, I, lds);
;         { const int dk = tid & 127, tq = tid >> 7; const float blast = bsh[63 * 128 + dk]; float ke[16];
;             bf16_t kraw[16];
; #pragma unroll
;             for (int i = 0; i < 16; ++i) { const int t = tq * 16 + i, tc = t < I.L ? t : I.L - 1; kraw[i] = kg[(size_t)(I.row0 + tc) * KEYD + I.h * DK + dk]; }
; #pragma unroll
;             for (int i = 0; i < 16; ++i) { const int t = tq * 16 + i; const float kv = bf1(kraw[i]) * __expf(blast - bsh[t * 128 + dk]); ke[i] = t < I.L ? kv : 0.f; }
;             u32x4 w0, w1; w0.x = cvt_pk_bf16(ke[0], ke[1]); w0.y = cvt_pk_bf16(ke[2], ke[3]); w0.z = cvt_pk_bf16(ke[4], ke[5]); w0.w = cvt_pk_bf16(ke[6], ke[7]);
;             w1.x = cvt_pk_bf16(ke[8], ke[9]); w1.y = cvt_pk_bf16(ke[10], ke[11]); w1.z = cvt_pk_bf16(ke[12], ke[13]); w1.w = cvt_pk_bf16(ke[14], ke[15]);
;             *(u32x4*)(kT + dk * 72 + tq * 16) = w0; *(u32x4*)(kT + dk * 72 + tq * 16 + 8) = w1;
.LBB0_1970:
	s_or_b64 exec, exec, s[48:49]
	v_add_f32_e32 v3, v17, v2
	v_add_f32_e32 v4, v18, v2
	ds_write2st64_b32 v113, v3, v4 offset0:16 offset1:18
	v_add_f32_e32 v3, v19, v2
	v_add_f32_e32 v4, v20, v2
	ds_write2st64_b32 v113, v3, v4 offset0:20 offset1:22
	v_add_f32_e32 v3, v21, v2
	v_add_f32_e32 v4, v22, v2
	ds_write2st64_b32 v113, v3, v4 offset0:24 offset1:26
	v_add_f32_e32 v3, v23, v2
	v_add_f32_e32 v4, v24, v2
	ds_write2st64_b32 v113, v3, v4 offset0:28 offset1:30
	v_add_f32_e32 v3, v25, v2
	v_add_f32_e32 v4, v26, v2
	ds_write2st64_b32 v113, v3, v4 offset0:32 offset1:34
	v_add_f32_e32 v3, v27, v2
	v_add_f32_e32 v4, v28, v2
	s_add_i32 s48, s64, -1
	ds_write2st64_b32 v113, v3, v4 offset0:36 offset1:38
	v_add_f32_e32 v3, v29, v2
	v_add_f32_e32 v4, v30, v2
	v_add_f32_e32 v0, v0, v2
	v_add_f32_e32 v1, v1, v2
	v_min_i32_e32 v2, s48, v95
	ds_write2st64_b32 v113, v3, v4 offset0:40 offset1:42
	v_add_u32_e32 v2, s82, v2
	v_min_i32_e32 v4, s48, v96
	s_lshl_b32 s76, s76, 1
	v_ashrrev_i32_e32 v3, 31, v2
	v_add_u32_e32 v4, s82, v4
	ds_write2st64_b32 v113, v0, v1 offset0:44 offset1:46
	v_lshl_add_u64 v[0:1], v[66:67], 0, s[76:77]
	v_lshlrev_b64 v[2:3], 10, v[2:3]
	v_ashrrev_i32_e32 v5, 31, v4
	v_lshl_add_u64 v[2:3], v[0:1], 0, v[2:3]
	v_lshlrev_b64 v[4:5], 10, v[4:5]
	s_waitcnt lgkmcnt(0)
	s_barrier
	v_lshlrev_b32_e32 v190, 6, v210
	v_add_u32_e32 v190, 0x1000, v190
	s_lshl_b32 s98, s65, 9
	v_lshrrev_b32_e32 v191, 3, v210
	v_add_u32_e32 v191, s82, v191
	v_lshlrev_b32_e32 v191, 11, v191
	v_and_b32_e32 v208, 7, v210
	v_lshl_add_u32 v208, v208, 6, s98
	v_add_u32_e32 v191, v191, v208
	s_add_u32 s100, s54, 0x308dc00
	s_addc_u32 s101, s55, 0
	s_mov_b32 s32, 0
	s_mov_b64 s[98:99], exec
	s_cmp_eq_u32 s64, 64
	s_cbranch_scc1 .Lg1_ball
	s_and_b64 exec, exec, s[8:9]
	s_cbranch_execz .Lg1_bskip
.Lg1_ball:
	s_mov_b32 s32, 1
	ds_read_b128 v[192:195], v190
	ds_read_b128 v[196:199], v190 offset:16
	ds_read_b128 v[200:203], v190 offset:32
	ds_read_b128 v[204:207], v190 offset:48
	s_waitcnt lgkmcnt(0)
	global_store_dwordx4 v191, v[192:195], s[100:101]
	global_store_dwordx4 v191, v[196:199], s[100:101] offset:16
	global_store_dwordx4 v191, v[200:203], s[100:101] offset:32
	global_store_dwordx4 v191, v[204:207], s[100:101] offset:48
.Lg1_bskip:
	s_mov_b64 exec, s[98:99]
	v_lshl_add_u64 v[4:5], v[0:1], 0, v[4:5]
	s_cmp_eq_u32 s32, 0
	s_cbranch_scc1 .Lg1w1_0
	s_cmp_eq_u32 s32, 1
	s_cbranch_scc1 .Lg1w1_1
	s_waitcnt vmcnt(8)
	s_branch .Lg1w1_e
.Lg1w1_1:
	s_waitcnt vmcnt(8)
	s_branch .Lg1w1_e
.Lg1w1_0:
	s_waitcnt vmcnt(4)
.Lg1w1_e:
	v_mov_b32_e32 v18, v212
	v_mov_b32_e32 v19, v213
	v_min_i32_e32 v6, s48, v97
	v_min_i32_e32 v10, s48, v101
	v_add_u32_e32 v6, s82, v6
	v_add_u32_e32 v10, s82, v10
	v_ashrrev_i32_e32 v7, 31, v6
	v_ashrrev_i32_e32 v11, 31, v10
	v_lshlrev_b64 v[6:7], 10, v[6:7]
	v_lshlrev_b64 v[10:11], 10, v[10:11]
	v_min_i32_e32 v12, s48, v102
	v_lshl_add_u64 v[6:7], v[0:1], 0, v[6:7]
	v_min_i32_e32 v8, s48, v98
	v_lshl_add_u64 v[10:11], v[0:1], 0, v[10:11]
	v_add_u32_e32 v12, s82, v12
	v_ashrrev_i32_e32 v13, 31, v12
	v_mov_b32_e32 v20, v214
	v_mov_b32_e32 v24, v218
	v_add_u32_e32 v2, s82, v8
	v_min_i32_e32 v4, s48, v99
	v_min_i32_e32 v8, s48, v100
	v_add_u32_e32 v4, s82, v4
	v_add_u32_e32 v8, s82, v8
	v_lshlrev_b64 v[6:7], 10, v[12:13]
	v_min_i32_e32 v12, s48, v103
	v_ashrrev_i32_e32 v3, 31, v2
	v_ashrrev_i32_e32 v5, 31, v4
	v_ashrrev_i32_e32 v9, 31, v8
	v_add_u32_e32 v12, s82, v12
	v_lshlrev_b64 v[2:3], 10, v[2:3]
	v_lshlrev_b64 v[4:5], 10, v[4:5]
	v_lshlrev_b64 v[8:9], 10, v[8:9]
	v_ashrrev_i32_e32 v13, 31, v12
	v_lshl_add_u64 v[2:3], v[0:1], 0, v[2:3]
	v_lshl_add_u64 v[4:5], v[0:1], 0, v[4:5]
	v_lshl_add_u64 v[8:9], v[0:1], 0, v[8:9]
	v_lshlrev_b64 v[12:13], 10, v[12:13]
	v_mov_b32_e32 v21, v215
	v_mov_b32_e32 v22, v216
	v_mov_b32_e32 v23, v217
	v_lshl_add_u64 v[2:3], v[0:1], 0, v[12:13]
	v_min_i32_e32 v12, s48, v104
	v_add_u32_e32 v4, s82, v12
	v_min_i32_e32 v12, s48, v105
	v_add_u32_e32 v12, s82, v12
	v_ashrrev_i32_e32 v13, 31, v12
	v_lshlrev_b64 v[12:13], 10, v[12:13]
	v_lshl_add_u64 v[8:9], v[0:1], 0, v[12:13]
	v_min_i32_e32 v12, s48, v106
	v_add_u32_e32 v10, s82, v12
	v_min_i32_e32 v12, s48, v107
	v_add_u32_e32 v12, s82, v12
	v_ashrrev_i32_e32 v13, 31, v12
	v_lshl_add_u64 v[6:7], v[0:1], 0, v[6:7]
	v_lshlrev_b64 v[12:13], 10, v[12:13]
	v_mov_b32_e32 v25, v219
	v_mov_b32_e32 v26, v220
	v_lshl_add_u64 v[6:7], v[0:1], 0, v[12:13]
	v_min_i32_e32 v12, s48, v108
	v_add_u32_e32 v2, s82, v12
	v_ashrrev_i32_e32 v3, 31, v2
	v_lshlrev_b64 v[2:3], 10, v[2:3]
	v_ashrrev_i32_e32 v5, 31, v4
	v_lshl_add_u64 v[12:13], v[0:1], 0, v[2:3]
	v_min_i32_e32 v2, s48, v109
	v_lshlrev_b64 v[4:5], 10, v[4:5]
	v_add_u32_e32 v2, s82, v2
	v_lshl_add_u64 v[4:5], v[0:1], 0, v[4:5]
	v_ashrrev_i32_e32 v3, 31, v2
	v_lshlrev_b64 v[14:15], 10, v[2:3]
	ds_read_b32 v2, v114 offset:4096
	ds_read_b32 v3, v113 offset:4096
	v_mov_b32_e32 v27, v221
	v_min_i32_e32 v16, s48, v110
	v_ashrrev_i32_e32 v11, 31, v10
	v_add_u32_e32 v16, s82, v16
	v_lshlrev_b64 v[10:11], 10, v[10:11]
	v_ashrrev_i32_e32 v17, 31, v16
	v_lshl_add_u64 v[10:11], v[0:1], 0, v[10:11]
	v_mov_b32_e32 v8, v222
	v_lshlrev_b64 v[4:5], 10, v[16:17]
	v_lshl_add_u64 v[14:15], v[0:1], 0, v[14:15]
	v_lshl_add_u64 v[0:1], v[0:1], 0, v[4:5]
	v_mov_b32_e32 v5, v223
	s_nop 0
	v_mov_b32_e32 v6, v224
	s_waitcnt lgkmcnt(0)
	v_sub_f32_e32 v3, v2, v3
	v_mul_f32_e32 v3, 0x3fb8aa3b, v3
	v_exp_f32_e32 v3, v3
	v_lshlrev_b32_e32 v4, 16, v18
	v_mul_f32_e32 v3, v3, v4
	v_lshlrev_b32_e32 v4, 16, v19
	ds_read_b32 v7, v133 offset:4096
	ds_read_b32 v9, v134 offset:4096
	ds_read_b32 v10, v135 offset:4096
	ds_read_b32 v11, v136 offset:4096
	ds_read_b32 v16, v137 offset:4096
	ds_read_b32 v17, v138 offset:4096
	ds_read_b32 v18, v139 offset:4096
	ds_read_b32 v19, v140 offset:4096
	v_mov_b32_e32 v12, v225
	s_waitcnt lgkmcnt(7)
; __device__ __forceinline__ unsigned cvt_pk_bf16(float lo, float hi) { unsigned r; asm volatile("v_cvt_pk_bf16_f32 %0, %1, %2" : "=v"(r) : "v"(lo), "v"(hi)); return r; }
; __device__ __forceinline__ float bf1(bf16_t b) { return __uint_as_float(((unsigned)b) << 16); }
; __device__ __forceinline__ void gla_g1(const Params& P, unsigned char* lds) {
;     ...
;             for (int i = 0; i < 16; ++i) { const int t = tq * 16 + i; const float kv = bf1(kraw[i]) * __expf(blast - bsh[t * 128 + dk]); ke[i] = t < I.L ? kv : 0.f; }
;             u32x4 w0, w1; w0.x = cvt_pk_bf16(ke[0], ke[1]); w0.y = cvt_pk_bf16(ke[2], ke[3]); w0.z = cvt_pk_bf16(ke[4], ke[5]); w0.w = cvt_pk_bf16(ke[6], ke[7]);
;             w1.x = cvt_pk_bf16(ke[8], ke[9]); w1.y = cvt_pk_bf16(ke[10], ke[11]); w1.z = cvt_pk_bf16(ke[12], ke[13]); w1.w = cvt_pk_bf16(ke[14], ke[15]);
;             *(u32x4*)(kT + dk * 72 + tq * 16) = w0; *(u32x4*)(kT + dk * 72 + tq * 16 + 8) = w1;
;             if (tq == 0) dec[(size_t)it * 128 + dk] = __expf(blast); }
;         __syncthreads();
;         f32x4 acc[8][2];
; #pragma unroll
;         for (int mt = 0; mt < 8; ++mt) { acc[mt][0] = (f32x4){0.f, 0.f, 0.f, 0.f}; acc[mt][1] = (f32x4){0.f, 0.f, 0.f, 0.f}; }
; #pragma unroll
;         for (int s = 0; s < 2; ++s) { const int t8 = 32 * s + 8 * fq;
;             if (32 * s < I.L) {
;                 bf16x8 bfr[2];
; #pragma unroll
;                 for (int nt = 0; nt < 2; ++nt) { const int tc = t8 < I.L ? t8 : 0; bfr[nt] = *(const bf16x8*)(vT + (size_t)(I.h * DV + 32 * wid + 16 * nt + fr) * MPAD + I.row0 + tc); if (t8 >= I.L) bfr[nt] = (bf16x8){0, 0, 0, 0, 0, 0, 0, 0}; }
; #pragma unroll
;                 for (int mt = 0; mt < 8; ++mt) { const bf16x8 a = *(const bf16x8*)(kT + (16 * mt + fr) * 72 + t8);
;                     acc[mt][0] = __builtin_amdgcn_mfma_f32_16x16x32_bf16(a, bfr[0], acc[mt][0], 0, 0, 0); acc[mt][1] = __builtin_amdgcn_mfma_f32_16x16x32_bf16(a, bfr[1], acc[mt][1], 0, 0, 0); } } }
	v_sub_f32_e32 v7, v2, v7
	v_mov_b32_e32 v0, v227
	v_mul_f32_e32 v7, 0x3fb8aa3b, v7
	v_mov_b32_e32 v13, v226
	s_waitcnt lgkmcnt(6)
	v_sub_f32_e32 v9, v2, v9
	v_exp_f32_e32 v7, v7
	v_mul_f32_e32 v9, 0x3fb8aa3b, v9
	v_exp_f32_e32 v9, v9
	s_waitcnt lgkmcnt(2)
	v_sub_f32_e32 v14, v2, v17
	v_mul_f32_e32 v4, v7, v4
	v_lshlrev_b32_e32 v7, 16, v20
	v_mul_f32_e32 v7, v9, v7
	v_sub_f32_e32 v9, v2, v10
	v_mul_f32_e32 v9, 0x3fb8aa3b, v9
	v_sub_f32_e32 v10, v2, v11
	v_exp_f32_e32 v9, v9
	v_mul_f32_e32 v10, 0x3fb8aa3b, v10
	v_exp_f32_e32 v10, v10
	v_sub_f32_e32 v11, v2, v16
	v_mul_f32_e32 v11, 0x3fb8aa3b, v11
	v_exp_f32_e32 v11, v11
	v_mul_f32_e32 v14, 0x3fb8aa3b, v14
	s_waitcnt lgkmcnt(1)
	v_sub_f32_e32 v15, v2, v18
	v_exp_f32_e32 v14, v14
	v_lshlrev_b32_e32 v1, 16, v21
	v_mul_f32_e32 v1, v9, v1
	v_lshlrev_b32_e32 v9, 16, v22
	v_mul_f32_e32 v9, v10, v9
	v_lshlrev_b32_e32 v10, 16, v23
	v_mul_f32_e32 v15, 0x3fb8aa3b, v15
	s_waitcnt lgkmcnt(0)
	v_sub_f32_e32 v16, v2, v19
	ds_read_b32 v17, v141 offset:4096
	ds_read_b32 v18, v142 offset:4096
	ds_read_b32 v19, v143 offset:4096
	ds_read_b32 v20, v144 offset:4096
	ds_read_b32 v21, v145 offset:4096
	ds_read_b32 v22, v146 offset:4096
	ds_read_b32 v23, v147 offset:4096
	v_exp_f32_e32 v15, v15
	v_mul_f32_e32 v16, 0x3fb8aa3b, v16
	s_waitcnt lgkmcnt(6)
	v_sub_f32_e32 v17, v2, v17
	v_exp_f32_e32 v16, v16
	v_mul_f32_e32 v17, 0x3fb8aa3b, v17
	v_mul_f32_e32 v10, v11, v10
	v_lshlrev_b32_e32 v11, 16, v24
	v_exp_f32_e32 v17, v17
	v_mul_f32_e32 v11, v14, v11
	v_cndmask_b32_e64 v4, 0, v4, s[16:17]
	v_lshlrev_b32_e32 v14, 16, v25
	v_mul_f32_e32 v14, v15, v14
	v_lshlrev_b32_e32 v15, 16, v26
	v_mul_f32_e32 v15, v16, v15
	v_cndmask_b32_e64 v7, 0, v7, s[18:19]
	v_cndmask_b32_e32 v3, 0, v3, vcc
	v_cndmask_b32_e64 v1, 0, v1, s[20:21]
	v_cndmask_b32_e64 v9, 0, v9, s[22:23]
	v_cndmask_b32_e64 v10, 0, v10, s[24:25]
	v_cndmask_b32_e64 v11, 0, v11, s[26:27]
	v_cndmask_b32_e64 v14, 0, v14, s[28:29]
	v_cvt_pk_bf16_f32 v4, v3, v4
	v_cndmask_b32_e64 v15, 0, v15, s[30:31]
	v_lshlrev_b32_e32 v16, 16, v27
	v_mul_f32_e32 v16, v17, v16
	s_waitcnt lgkmcnt(5)
	v_sub_f32_e32 v17, v2, v18
	s_waitcnt lgkmcnt(4)
	v_sub_f32_e32 v18, v2, v19
	v_mul_f32_e32 v18, 0x3fb8aa3b, v18
	v_exp_f32_e32 v18, v18
	v_mul_f32_e32 v17, 0x3fb8aa3b, v17
	v_exp_f32_e32 v17, v17
	v_lshlrev_b32_e32 v8, 16, v8
	v_cndmask_b32_e64 v16, 0, v16, s[34:35]
	v_lshlrev_b32_e32 v5, 16, v5
	v_mul_f32_e32 v5, v18, v5
	v_cndmask_b32_e64 v18, 0, v5, s[38:39]
	v_lshlrev_b32_e32 v5, 16, v6
	s_waitcnt lgkmcnt(3)
	v_sub_f32_e32 v6, v2, v20
	v_mul_f32_e32 v8, v17, v8
	v_mul_f32_e32 v6, 0x3fb8aa3b, v6
	v_cndmask_b32_e64 v17, 0, v8, s[36:37]
	v_exp_f32_e32 v6, v6
	s_waitcnt lgkmcnt(2)
	v_sub_f32_e32 v8, v2, v21
	v_mul_f32_e32 v8, 0x3fb8aa3b, v8
	v_exp_f32_e32 v8, v8
	v_mul_f32_e32 v5, v6, v5
	v_cndmask_b32_e64 v19, 0, v5, s[40:41]
	v_lshlrev_b32_e32 v5, 16, v12
	s_waitcnt lgkmcnt(1)
	v_sub_f32_e32 v6, v2, v22
	v_mul_f32_e32 v5, v8, v5
	v_mul_f32_e32 v6, 0x3fb8aa3b, v6
	s_waitcnt lgkmcnt(0)
	v_sub_f32_e32 v8, v2, v23
	v_exp_f32_e32 v6, v6
	v_mul_f32_e32 v8, 0x3fb8aa3b, v8
	v_exp_f32_e32 v8, v8
	v_cndmask_b32_e64 v12, 0, v5, s[42:43]
	v_lshlrev_b32_e32 v5, 16, v13
	v_mul_f32_e32 v5, v6, v5
	v_lshlrev_b32_e32 v0, 16, v0
	v_cndmask_b32_e64 v13, 0, v5, s[44:45]
	v_mul_f32_e32 v0, v8, v0
	v_cvt_pk_bf16_f32 v5, v7, v1
	v_cvt_pk_bf16_f32 v6, v9, v10
	v_cvt_pk_bf16_f32 v7, v11, v14
	v_cndmask_b32_e64 v0, 0, v0, s[46:47]
	v_cvt_pk_bf16_f32 v8, v15, v16
	v_cvt_pk_bf16_f32 v9, v17, v18
	v_cvt_pk_bf16_f32 v10, v19, v12
	v_cvt_pk_bf16_f32 v11, v13, v0
	ds_write_b128 v115, v[4:7] offset:38912
	ds_write_b128 v115, v[8:11] offset:38928
	s_and_saveexec_b64 s[16:17], s[8:9]
	s_cbranch_execz .LBB0_1972
	v_mul_f32_e32 v0, 0x3fb8aa3b, v2
	v_exp_f32_e32 v2, v0
	s_ashr_i32 s79, s78, 31
	s_lshl_b64 s[18:19], s[78:79], 9
	v_lshl_add_u64 v[0:1], v[68:69], 0, s[18:19]
	global_store_dword v[0:1], v2, off
	s_bitset1_b32 s32, 1
.LBB0_1972:
	s_or_b64 exec, exec, s[16:17]
	s_ashr_i32 s83, s82, 31
	s_lshl_b64 s[16:17], s[82:83], 1
	v_cmp_gt_u32_e32 vcc, s64, v70
	s_add_u32 s18, s3, s16
	v_lshl_add_u32 v2, s65, 8, v116
	v_cndmask_b32_e32 v0, 0, v70, vcc
	s_addc_u32 s19, s85, s17
	v_lshlrev_b32_e32 v64, 1, v0
	v_lshl_add_u64 v[0:1], s[18:19], 0, v[64:65]
	v_mul_u32_u24_e32 v64, 0x8280, v2
	v_lshl_add_u64 v[4:5], v[0:1], 0, v[64:65]
	s_waitcnt lgkmcnt(0)
	s_barrier
	s_cmp_eq_u32 s32, 0
	s_cbranch_scc1 .Lg1w2_0
	s_cmp_eq_u32 s32, 1
	s_cbranch_scc1 .Lg1w2_1
	s_waitcnt vmcnt(7)
	s_branch .Lg1w2_e
.Lg1w2_1:
	s_waitcnt vmcnt(6)
	s_branch .Lg1w2_e
.Lg1w2_0:
	s_waitcnt vmcnt(2)
.Lg1w2_e:
	v_mov_b32_e32 v0, v228
	v_mov_b32_e32 v1, v229
	v_mov_b32_e32 v2, v230
	v_mov_b32_e32 v3, v231
	v_add_co_u32_e64 v4, s[16:17], s84, v4
	v_cndmask_b32_e32 v3, 0, v3, vcc
	v_addc_co_u32_e64 v5, s[16:17], 0, v5, s[16:17]
	v_mov_b32_e32 v4, v232
	v_mov_b32_e32 v5, v233
	v_mov_b32_e32 v6, v234
	v_mov_b32_e32 v7, v235
	ds_read_b128 v[12:15], v149 offset:38912
	ds_read_b128 v[20:23], v149 offset:41216
	ds_read_b128 v[28:31], v149 offset:43520
	ds_read_b128 v[36:39], v149 offset:45824
	ds_read_b128 v[150:153], v149 offset:48128
	ds_read_b128 v[154:157], v149 offset:50432
	ds_read_b128 v[158:161], v149 offset:52736
	ds_read_b128 v[162:165], v149 offset:55040
	v_cndmask_b32_e32 v2, 0, v2, vcc
	v_cndmask_b32_e32 v1, 0, v1, vcc
	v_cndmask_b32_e32 v0, 0, v0, vcc
	v_cndmask_b32_e32 v7, 0, v7, vcc
	v_cndmask_b32_e32 v6, 0, v6, vcc
	v_cndmask_b32_e32 v5, 0, v5, vcc
	v_cndmask_b32_e32 v4, 0, v4, vcc
	s_waitcnt lgkmcnt(7)
	v_mfma_f32_16x16x32_bf16 v[56:59], v[12:15], v[0:3], 0
	s_andn2_b64 vcc, exec, s[80:81]
	s_waitcnt lgkmcnt(6)
	v_mfma_f32_16x16x32_bf16 v[48:51], v[20:23], v[0:3], 0
	s_waitcnt lgkmcnt(5)
	v_mfma_f32_16x16x32_bf16 v[40:43], v[28:31], v[0:3], 0
	s_waitcnt lgkmcnt(4)
	v_mfma_f32_16x16x32_bf16 v[32:35], v[36:39], v[0:3], 0
	s_waitcnt lgkmcnt(3)
	v_mfma_f32_16x16x32_bf16 v[24:27], v[150:153], v[0:3], 0
	s_waitcnt lgkmcnt(2)
	v_mfma_f32_16x16x32_bf16 v[16:19], v[154:157], v[0:3], 0
	s_waitcnt lgkmcnt(1)
	v_mfma_f32_16x16x32_bf16 v[8:11], v[158:161], v[0:3], 0
	s_waitcnt lgkmcnt(0)
	v_mfma_f32_16x16x32_bf16 v[0:3], v[162:165], v[0:3], 0
	v_mfma_f32_16x16x32_bf16 v[60:63], v[12:15], v[4:7], 0
	v_mfma_f32_16x16x32_bf16 v[52:55], v[20:23], v[4:7], 0
	v_mfma_f32_16x16x32_bf16 v[44:47], v[28:31], v[4:7], 0
	v_mfma_f32_16x16x32_bf16 v[36:39], v[36:39], v[4:7], 0
	v_mfma_f32_16x16x32_bf16 v[28:31], v[150:153], v[4:7], 0
	v_mfma_f32_16x16x32_bf16 v[20:23], v[154:157], v[4:7], 0
	v_mfma_f32_16x16x32_bf16 v[12:15], v[158:161], v[4:7], 0
	v_mfma_f32_16x16x32_bf16 v[4:7], v[162:165], v[4:7], 0
	s_cbranch_vccnz .LBB0_1961
	v_cmp_gt_u32_e64 s[16:17], s64, v71
	v_mov_b32_e32 v151, v65
	s_nop 0
	v_cndmask_b32_e64 v150, 0, v71, s[16:17]
	v_lshlrev_b32_e32 v150, 1, v150
	v_lshl_add_u64 v[150:151], s[18:19], 0, v[150:151]
	v_lshl_add_u64 v[154:155], v[150:151], 0, v[64:65]
	s_cmp_eq_u32 s32, 0
	s_cbranch_scc1 .Lg1w3_0
	s_cmp_eq_u32 s32, 1
	s_cbranch_scc1 .Lg1w3_1
	s_waitcnt vmcnt(5)
	s_branch .Lg1w3_e
.Lg1w3_1:
	s_waitcnt vmcnt(4)
	s_branch .Lg1w3_e

; __device__ __forceinline__ void gla_g1(const Params& P, unsigned char* lds) {
;     ...
; #pragma unroll
;         for (int s = 0; s < 2; ++s) { const int t8 = 32 * s + 8 * fq;
;             if (32 * s < I.L) {
;                 bf16x8 bfr[2];
; #pragma unroll
;                 for (int nt = 0; nt < 2; ++nt) { const int tc = t8 < I.L ? t8 : 0; bfr[nt] = *(const bf16x8*)(vT + (size_t)(I.h * DV + 32 * wid + 16 * nt + fr) * MPAD + I.row0 + tc); if (t8 >= I.L) bfr[nt] = (bf16x8){0, 0, 0, 0, 0, 0, 0, 0}; }
; #pragma unroll
;                 for (int mt = 0; mt < 8; ++mt) { const bf16x8 a = *(const bf16x8*)(kT + (16 * mt + fr) * 72 + t8);
;                     acc[mt][0] = __builtin_amdgcn_mfma_f32_16x16x32_bf16(a, bfr[0], acc[mt][0], 0, 0, 0); acc[mt][1] = __builtin_amdgcn_mfma_f32_16x16x32_bf16(a, bfr[1], acc[mt][1], 0, 0, 0); } } }
.Lg1w3_e:
	v_mov_b32_e32 v150, v236
	v_mov_b32_e32 v151, v237
	v_mov_b32_e32 v152, v238
	v_mov_b32_e32 v153, v239
	v_add_co_u32_e32 v154, vcc, 0x82000, v154
	v_cndmask_b32_e64 v153, 0, v153, s[16:17]
	v_addc_co_u32_e32 v155, vcc, 0, v155, vcc
	v_mov_b32_e32 v154, v244
	v_mov_b32_e32 v155, v245
	v_mov_b32_e32 v156, v246
	v_mov_b32_e32 v157, v247
	ds_read_b128 v[158:161], v149 offset:38976
	ds_read_b128 v[162:165], v149 offset:41280
	ds_read_b128 v[166:169], v149 offset:43584
	ds_read_b128 v[170:173], v149 offset:45888
	ds_read_b128 v[174:177], v149 offset:48192
	ds_read_b128 v[178:181], v149 offset:50496
	ds_read_b128 v[182:185], v149 offset:52800
	ds_read_b128 v[186:189], v149 offset:55104
	v_cndmask_b32_e64 v152, 0, v152, s[16:17]
	v_cndmask_b32_e64 v151, 0, v151, s[16:17]
	v_cndmask_b32_e64 v150, 0, v150, s[16:17]
	s_waitcnt lgkmcnt(7)
	s_nop 0
	v_mfma_f32_16x16x32_bf16 v[56:59], v[158:161], v[150:153], v[56:59]
	s_waitcnt lgkmcnt(6)
	v_mfma_f32_16x16x32_bf16 v[48:51], v[162:165], v[150:153], v[48:51]
	s_waitcnt lgkmcnt(5)
	v_mfma_f32_16x16x32_bf16 v[40:43], v[166:169], v[150:153], v[40:43]
	s_waitcnt lgkmcnt(4)
	v_mfma_f32_16x16x32_bf16 v[32:35], v[170:173], v[150:153], v[32:35]
	s_waitcnt lgkmcnt(3)
	v_mfma_f32_16x16x32_bf16 v[24:27], v[174:177], v[150:153], v[24:27]
	s_waitcnt lgkmcnt(2)
	v_mfma_f32_16x16x32_bf16 v[16:19], v[178:181], v[150:153], v[16:19]
	s_waitcnt lgkmcnt(1)
	v_mfma_f32_16x16x32_bf16 v[8:11], v[182:185], v[150:153], v[8:11]
	s_waitcnt lgkmcnt(0)
	v_mfma_f32_16x16x32_bf16 v[0:3], v[186:189], v[150:153], v[0:3]
	v_cndmask_b32_e64 v153, 0, v157, s[16:17]
	v_cndmask_b32_e64 v152, 0, v156, s[16:17]
	v_cndmask_b32_e64 v151, 0, v155, s[16:17]
	v_cndmask_b32_e64 v150, 0, v154, s[16:17]
	s_nop 1
	v_mfma_f32_16x16x32_bf16 v[60:63], v[158:161], v[150:153], v[60:63]
	v_mfma_f32_16x16x32_bf16 v[52:55], v[162:165], v[150:153], v[52:55]
	v_mfma_f32_16x16x32_bf16 v[44:47], v[166:169], v[150:153], v[44:47]
	v_mfma_f32_16x16x32_bf16 v[36:39], v[170:173], v[150:153], v[36:39]
	v_mfma_f32_16x16x32_bf16 v[28:31], v[174:177], v[150:153], v[28:31]
	v_mfma_f32_16x16x32_bf16 v[20:23], v[178:181], v[150:153], v[20:23]
	v_mfma_f32_16x16x32_bf16 v[12:15], v[182:185], v[150:153], v[12:15]
	v_mfma_f32_16x16x32_bf16 v[4:7], v[186:189], v[150:153], v[4:7]
	s_branch .LBB0_1961
